# static priority raise (s_setprio 1) for waves 0-3 over the whole diff-attention fast loop, reset in the exit stubs
# baseline (speedup 1.0000x reference)
; #define WAIT_BAR(N) asm volatile("s_waitcnt vmcnt(" #N ") lgkmcnt(0)\n\ts_barrier":::"memory")
;   #define RESC() do{ if(resc){ asm volatile("s_waitcnt lgkmcnt(0)":::"memory"); \
;       _Pragma("unroll") for(int d_=0;d_<2;++d_) _Pragma("unroll") for(int r=0;r<16;++r)o[d_][r]*=wsf[crow(r,hi)]; } }while(0)
;   #define ROT() do{sl_prev=sl_cur;sl_cur=sl_next;sl_next=(sl_next==(NSLOT-1)*SLOTB)?0:sl_next+SLOTB;}while(0)
;     ...
;   for(;t+5<NT;t+=2){
;     STEP(pB0,pB1,pA0,pA1,t,true,true,true);     WAIT_BAR(2); RESC(); ROT();
;     STEP(pA0,pA1,pB0,pB1,t+1,true,true,true);   WAIT_BAR(2); RESC(); ROT();
;   }
.Lfb_pre:
	v_readfirstlane_b32 s0, v230
	s_nop 3
	s_lshr_b32 s0, s0, 6
	s_cmp_ge_u32 s0, 4
	s_cbranch_scc1 .Lfb_noprio
	s_setprio 1
